# E-phase past-row k-norm loop: 5 loads issued together, one wait (plus G2 loop rewrite and lean past-K epilogue)
# baseline (speedup 1.0000x reference)
.LBB0_766:
	v_add_co_u32_e32 v20, vcc, 0x800000, v14
	global_load_dwordx4 v[8:11], v[14:15], off
	s_nop 0
	v_addc_co_u32_e32 v21, vcc, 0, v15, vcc
	global_load_dwordx4 v[20:23], v[20:21], off
	v_and_b32_e32 v19, 0xffc, v16
	v_and_b32_e32 v2, 0x7c000, v12
	v_lshl_add_u64 v[12:13], v[12:13], 0, s[16:17]
	v_lshl_add_u64 v[16:17], v[16:17], 0, s[24:25]
	v_add_co_u32_e32 v40, vcc, 0x1000000, v14
	s_nop 1
	v_addc_co_u32_e32 v41, vcc, 0, v15, vcc
	v_add_co_u32_e32 v42, vcc, 0x1800000, v14
	global_load_dwordx4 v[44:47], v[40:41], off
	s_nop 0
	v_addc_co_u32_e32 v43, vcc, 0, v15, vcc
	global_load_dwordx4 v[48:51], v[42:43], off
	v_lshl_add_u64 v[40:41], s[20:21], 0, v[2:3]
	v_lshlrev_b32_e32 v2, 2, v19
	v_lshl_add_u64 v[40:41], v[40:41], 0, v[2:3]
	global_load_dwordx4 v[52:55], v[40:41], off
	s_waitcnt vmcnt(0)
	v_pk_add_f32 v[26:27], v[8:9], v[20:21]
	v_pk_add_f32 v[24:25], v[10:11], v[22:23]
	v_pk_add_f32 v[8:9], v[44:45], v[48:49]
	v_pk_add_f32 v[10:11], v[46:47], v[50:51]
	v_pk_add_f32 v[22:23], v[26:27], v[8:9]
	v_pk_add_f32 v[20:21], v[24:25], v[10:11]
	v_pk_add_f32 v[8:9], v[52:53], v[22:23]
	s_nop 0
	v_fmamk_f32 v2, v8, 0x3baaaaab, v201
	v_cmp_gt_f32_e32 vcc, s91, v2
	v_mul_f32_e32 v8, 0x4f800000, v2
	v_pk_add_f32 v[10:11], v[54:55], v[20:21]
	v_cndmask_b32_e32 v2, v2, v8, vcc
	v_sqrt_f32_e32 v8, v2
	s_nop 0
	v_add_u32_e32 v19, -1, v8
	v_fma_f32 v20, -v19, v8, v2
	v_cmp_ge_f32_e64 s[42:43], 0, v20
	v_add_u32_e32 v20, 1, v8
	s_nop 0
	v_cndmask_b32_e64 v19, v8, v19, s[42:43]
	v_fma_f32 v8, -v20, v8, v2
	v_cmp_lt_f32_e64 s[42:43], 0, v8
	s_nop 1
	v_cndmask_b32_e64 v8, v19, v20, s[42:43]
	v_mul_f32_e32 v19, 0x37800000, v8
	v_cndmask_b32_e32 v8, v8, v19, vcc
	v_cmp_class_f32_e32 vcc, v2, v202
	s_nop 1
	v_cndmask_b32_e32 v2, v8, v2, vcc
	v_div_scale_f32 v8, s[4:5], v2, v2, 1.0
	v_rcp_f32_e32 v19, v8
	s_nop 0
	v_fma_f32 v20, -v8, v19, 1.0
	v_fmac_f32_e32 v19, v20, v19
	v_div_scale_f32 v20, vcc, 1.0, v2, 1.0
	v_mul_f32_e32 v21, v20, v19
	v_fma_f32 v22, -v8, v21, v20
	v_fmac_f32_e32 v21, v22, v19
	v_fma_f32 v8, -v8, v21, v20
	v_div_fmas_f32 v8, v8, v19, v21
	v_div_fixup_f32 v8, v8, v2, 1.0
	v_fmamk_f32 v2, v9, 0x3baaaaab, v201
	v_cmp_gt_f32_e32 vcc, s91, v2
	v_mul_f32_e32 v9, 0x4f800000, v2
	s_nop 0
	v_cndmask_b32_e32 v2, v2, v9, vcc
	v_sqrt_f32_e32 v9, v2
	s_nop 0
	v_add_u32_e32 v19, -1, v9
	v_fma_f32 v20, -v19, v9, v2
	v_cmp_ge_f32_e64 s[42:43], 0, v20
	v_add_u32_e32 v20, 1, v9
	s_nop 0
	v_cndmask_b32_e64 v19, v9, v19, s[42:43]
	v_fma_f32 v9, -v20, v9, v2
	v_cmp_lt_f32_e64 s[42:43], 0, v9
	s_nop 1
	v_cndmask_b32_e64 v9, v19, v20, s[42:43]
	v_mul_f32_e32 v19, 0x37800000, v9
	v_cndmask_b32_e32 v9, v9, v19, vcc
	v_cmp_class_f32_e32 vcc, v2, v202
	s_nop 1
	v_cndmask_b32_e32 v2, v9, v2, vcc
	v_div_scale_f32 v9, s[4:5], v2, v2, 1.0
	v_rcp_f32_e32 v19, v9
	s_nop 0
	v_fma_f32 v20, -v9, v19, 1.0
	v_fmac_f32_e32 v19, v20, v19
	v_div_scale_f32 v20, vcc, 1.0, v2, 1.0
	v_mul_f32_e32 v21, v20, v19
	v_fma_f32 v22, -v9, v21, v20
	v_fmac_f32_e32 v21, v22, v19
	v_fma_f32 v9, -v9, v21, v20
	v_div_fmas_f32 v9, v9, v19, v21
	v_div_fixup_f32 v9, v9, v2, 1.0
	v_fmamk_f32 v2, v10, 0x3baaaaab, v201
	v_cmp_gt_f32_e32 vcc, s91, v2
	v_mul_f32_e32 v10, 0x4f800000, v2
	s_nop 0
	v_cndmask_b32_e32 v2, v2, v10, vcc
	v_sqrt_f32_e32 v10, v2
	s_nop 0
	v_add_u32_e32 v19, -1, v10
	v_fma_f32 v20, -v19, v10, v2
	v_cmp_ge_f32_e64 s[42:43], 0, v20
	v_add_u32_e32 v20, 1, v10
	s_nop 0
	v_cndmask_b32_e64 v19, v10, v19, s[42:43]
	v_fma_f32 v10, -v20, v10, v2
	v_cmp_lt_f32_e64 s[42:43], 0, v10
	s_nop 1
	v_cndmask_b32_e64 v10, v19, v20, s[42:43]
	v_mul_f32_e32 v19, 0x37800000, v10
	v_cndmask_b32_e32 v10, v10, v19, vcc
	v_cmp_class_f32_e32 vcc, v2, v202
	s_nop 1
	v_cndmask_b32_e32 v2, v10, v2, vcc
	v_div_scale_f32 v10, s[4:5], v2, v2, 1.0
	v_rcp_f32_e32 v19, v10
	s_nop 0
	v_fma_f32 v20, -v10, v19, 1.0
	v_fmac_f32_e32 v19, v20, v19
	v_div_scale_f32 v20, vcc, 1.0, v2, 1.0
	v_mul_f32_e32 v21, v20, v19
	v_fma_f32 v22, -v10, v21, v20
	v_fmac_f32_e32 v21, v22, v19
	v_fma_f32 v10, -v10, v21, v20
	v_div_fmas_f32 v10, v10, v19, v21
	v_div_fixup_f32 v10, v10, v2, 1.0
	v_fmamk_f32 v2, v11, 0x3baaaaab, v201
	v_cmp_gt_f32_e32 vcc, s91, v2
	v_mul_f32_e32 v11, 0x4f800000, v2
	s_nop 0
	v_cndmask_b32_e32 v2, v2, v11, vcc
	v_sqrt_f32_e32 v11, v2
	s_nop 0
	v_add_u32_e32 v19, -1, v11
	v_fma_f32 v20, -v19, v11, v2
	v_cmp_ge_f32_e64 s[42:43], 0, v20
	v_add_u32_e32 v20, 1, v11
	s_nop 0
	v_cndmask_b32_e64 v19, v11, v19, s[42:43]
	v_fma_f32 v11, -v20, v11, v2
	v_cmp_lt_f32_e64 s[42:43], 0, v11
	s_nop 1
	v_cndmask_b32_e64 v11, v19, v20, s[42:43]
	v_mul_f32_e32 v19, 0x37800000, v11
	v_cndmask_b32_e32 v11, v11, v19, vcc
	v_cmp_class_f32_e32 vcc, v2, v202
	s_nop 1
	v_cndmask_b32_e32 v2, v11, v2, vcc
	v_div_scale_f32 v11, s[4:5], v2, v2, 1.0
	v_rcp_f32_e32 v19, v11
	s_mov_b64 s[4:5], 0x7ffff
	v_fma_f32 v20, -v11, v19, 1.0
	v_fmac_f32_e32 v19, v20, v19
	v_div_scale_f32 v20, vcc, 1.0, v2, 1.0
	v_mul_f32_e32 v21, v20, v19
	v_fma_f32 v22, -v11, v21, v20
	v_fmac_f32_e32 v21, v22, v19
	v_fma_f32 v11, -v11, v21, v20
	v_div_fmas_f32 v11, v11, v19, v21
	v_add_co_u32_e32 v20, vcc, 0x2bc6a000, v14
	v_div_fixup_f32 v11, v11, v2, 1.0
	s_nop 0
	v_addc_co_u32_e32 v21, vcc, 0, v15, vcc
	v_cmp_lt_u64_e32 vcc, s[4:5], v[12:13]
	v_lshl_add_u64 v[14:15], v[14:15], 0, s[22:23]
	s_or_b64 s[26:27], vcc, s[26:27]
	global_store_dwordx4 v[20:21], v[8:11], off
	s_andn2_b64 exec, exec, s[26:27]
	s_cbranch_execnz .LBB0_766
